# GEMM phase prologues: K-tile 1 LDS-DMA loads issued right behind K-tile 0's (wait+barrier moved below them)
# speedup vs baseline: 1.0068x; 1.0008x over previous
.LBB0_118:
	s_add_u32 s12, s6, 0x4000000
	s_addc_u32 s13, s7, 0
	s_lshl_b32 s14, s14, 5
	s_and_b32 s61, s14, 0x60
	s_mov_b64 s[14:15], 0x80
	s_add_i32 m0, s48, 0x18000
	v_lshl_add_u64 v[8:9], v[8:9], 0, s[14:15]
	s_lshl_b32 s60, s5, 6
	s_lshl_b32 s5, s5, 13
	s_lshl_b32 s19, s61, 7
	global_load_lds_dwordx4 v[8:9], off
	v_lshl_add_u64 v[6:7], v[6:7], 0, s[14:15]
	s_add_i32 m0, s48, 0x1a000
	s_add_i32 s62, s48, 0x8000
	s_add_i32 s63, s48, 0xa000
	global_load_lds_dwordx4 v[6:7], off
	v_lshl_add_u64 v[2:3], v[2:3], 0, s[14:15]
	s_mov_b32 m0, s62
	s_add_u32 s20, s34, 0x40080
	global_load_lds_dwordx4 v[2:3], off
	v_lshl_add_u64 v[2:3], v[4:5], 0, s[14:15]
	s_mov_b32 m0, s63
	s_addc_u32 s21, s35, 0
	global_load_lds_dwordx4 v[2:3], off
	s_add_i32 m0, s48, 0x1c000
	v_lshl_add_u64 v[2:3], s[20:21], 0, v[132:133]
	global_load_lds_dwordx4 v[2:3], off
	v_lshl_add_u64 v[2:3], s[20:21], 0, v[136:137]
	s_add_i32 m0, s48, 0x1e000
	s_movk_i32 s20, 0x3c0
	global_load_lds_dwordx4 v[2:3], off
	s_waitcnt vmcnt(8)
	s_barrier
	v_and_b32_e32 v2, 48, v10
	v_lshlrev_b32_e32 v3, 6, v10
	v_and_or_b32 v2, v3, s20, v2
	v_lshlrev_b32_e32 v3, 2, v10
	v_and_b32_e32 v3, 32, v3
	v_bitop3_b32 v4, v2, s5, v3 bitop3:0xde
	v_bitop3_b32 v158, s19, v2, v3 bitop3:0xf6
	v_lshlrev_b32_e32 v2, 14, v11
	v_and_b32_e32 v2, 0xffff8000, v2
	v_lshl_add_u32 v2, v12, 11, v2
	v_and_b32_e32 v3, 1, v11
	v_lshl_or_b32 v2, v3, 6, v2
	s_load_dwordx2 s[16:17], s[16:17], 0x68
	v_lshl_add_u32 v140, v13, 1, v2
	v_lshlrev_b32_e32 v2, 14, v14
	v_and_b32_e32 v2, 0xffff8000, v2
	s_waitcnt vmcnt(6)
	s_cmpk_lt_u32 s18, 0x100
	v_lshl_add_u32 v2, v15, 11, v2
	v_and_b32_e32 v3, 1, v14
	s_cselect_b64 s[18:19], -1, 0
	v_lshl_or_b32 v2, v3, 6, v2
	s_add_i32 s65, 0, 0x10000
	s_add_i32 s66, 0, 0x14000
	s_mov_b32 s64, s52
	v_mov_b32_e32 v141, v139
	v_lshl_add_u32 v142, v16, 1, v2
	v_mov_b32_e32 v143, v139
	v_mov_b64_e32 v[144:145], 0x300
	s_mov_b64 s[20:21], 0x100
	v_add_u32_e32 v159, s65, v158
	v_add_u32_e32 v160, s66, v158
	v_add_u32_e32 v161, 0, v4
	s_movk_i32 s67, 0x1800
	v_mov_b64_e32 v[146:147], 0x200
	s_barrier
	s_branch .LBB0_121

.LBB0_752:
	v_and_b32_e32 v17, 15, v10
	v_and_b32_e32 v18, 48, v10
	v_lshlrev_b32_e32 v10, 2, v10
	s_mov_b64 s[18:19], 0x80
	s_and_b32 s49, s33, 3
	v_lshl_or_b32 v17, v17, 6, v18
	s_lshl_b32 s4, s47, 13
	v_and_b32_e32 v10, 32, v10
	s_add_i32 m0, s15, 0x18000
	v_lshl_add_u64 v[8:9], v[8:9], 0, s[18:19]
	v_bitop3_b32 v18, v17, s4, v10 bitop3:0xde
	s_lshl_b32 s4, s49, 12
	global_load_lds_dwordx4 v[8:9], off
	v_lshl_add_u64 v[6:7], v[6:7], 0, s[18:19]
	s_add_i32 m0, s15, 0x1a000
	s_add_i32 s60, s15, 0x8000
	s_add_i32 s61, s15, 0xa000
	global_load_lds_dwordx4 v[6:7], off
	v_lshl_add_u64 v[4:5], v[4:5], 0, s[18:19]
	s_mov_b32 m0, s60
	s_add_u32 s6, s26, 0x80080
	global_load_lds_dwordx4 v[4:5], off
	v_lshl_add_u64 v[2:3], v[2:3], 0, s[18:19]
	s_mov_b32 m0, s61
	s_addc_u32 s7, s27, 0
	global_load_lds_dwordx4 v[2:3], off
	s_add_i32 m0, s15, 0x1c000
	v_lshl_add_u64 v[2:3], s[6:7], 0, v[132:133]
	global_load_lds_dwordx4 v[2:3], off
	v_lshl_add_u64 v[2:3], s[6:7], 0, v[136:137]
	s_add_i32 m0, s15, 0x1e000
	v_bitop3_b32 v150, v17, s4, v10 bitop3:0xde
	global_load_lds_dwordx4 v[2:3], off
	s_waitcnt vmcnt(8)
	s_barrier
	v_lshlrev_b32_e32 v2, 15, v11
	v_and_b32_e32 v2, 0xffff0000, v2
	v_lshl_add_u32 v2, v12, 12, v2
	v_and_b32_e32 v3, 1, v11
	v_lshl_or_b32 v2, v3, 6, v2
	s_mov_b64 s[4:5], 0x80080
	v_lshl_add_u32 v2, v13, 1, v2
	v_mov_b32_e32 v3, v133
	v_lshl_add_u64 v[138:139], v[2:3], 0, s[4:5]
	v_lshlrev_b32_e32 v2, 15, v14
	v_and_b32_e32 v2, 0xffff0000, v2
	v_lshl_add_u32 v2, v15, 12, v2
	v_and_b32_e32 v3, 1, v14
	s_waitcnt vmcnt(6)
	v_lshl_or_b32 v2, v3, 6, v2
	v_lshl_add_u32 v2, v16, 1, v2
	v_mov_b32_e32 v3, v133
	v_lshl_add_u64 v[140:141], v[2:3], 0, s[4:5]
	v_mov_b64_e32 v[142:143], 0x100
	v_mov_b64_e32 v[144:145], 0xff
	s_add_i32 s62, 0, 0x10000
	s_add_i32 s63, 0, 0x14000
	v_add_u32_e32 v151, 0, v18
	v_mov_b32_e32 v2, v133
	v_mov_b32_e32 v4, v133
	v_mov_b32_e32 v5, v133
	v_mov_b32_e32 v6, v133
	v_mov_b32_e32 v7, v133
	v_mov_b32_e32 v8, v133
	v_mov_b32_e32 v9, v133
	v_mov_b32_e32 v10, v133
	v_mov_b32_e32 v11, v133
	v_mov_b32_e32 v12, v133
	v_mov_b32_e32 v13, v133
	v_mov_b32_e32 v14, v133
	v_mov_b32_e32 v15, v133
	v_mov_b32_e32 v16, v133
	v_mov_b32_e32 v17, v133
	v_mov_b32_e32 v34, v133
	v_mov_b32_e32 v35, v133
	v_mov_b32_e32 v36, v133
	v_mov_b32_e32 v37, v133
	v_mov_b32_e32 v38, v133
	v_mov_b32_e32 v39, v133
	v_mov_b32_e32 v40, v133
	v_mov_b32_e32 v41, v133
	v_mov_b32_e32 v42, v133
	v_mov_b32_e32 v43, v133
	v_mov_b32_e32 v44, v133
	v_mov_b32_e32 v45, v133
	v_mov_b32_e32 v46, v133
	v_mov_b32_e32 v47, v133
	v_mov_b32_e32 v48, v133
	v_mov_b32_e32 v49, v133
	v_mov_b32_e32 v18, v133
	v_mov_b32_e32 v19, v133
	v_mov_b32_e32 v20, v133
	v_mov_b32_e32 v21, v133
	v_mov_b32_e32 v22, v133
	v_mov_b32_e32 v23, v133
	v_mov_b32_e32 v24, v133
	v_mov_b32_e32 v25, v133
	v_mov_b32_e32 v26, v133
	v_mov_b32_e32 v27, v133
	v_mov_b32_e32 v28, v133
	v_mov_b32_e32 v29, v133
	v_mov_b32_e32 v30, v133
	v_mov_b32_e32 v31, v133
	v_mov_b32_e32 v32, v133
	v_mov_b32_e32 v33, v133
	v_mov_b32_e32 v50, v133
	v_mov_b32_e32 v51, v133
	v_mov_b32_e32 v52, v133
	v_mov_b32_e32 v53, v133
	v_mov_b32_e32 v54, v133
	v_mov_b32_e32 v55, v133
	v_mov_b32_e32 v56, v133
	v_mov_b32_e32 v57, v133
	v_mov_b32_e32 v58, v133
	v_mov_b32_e32 v59, v133
	v_mov_b32_e32 v60, v133
	v_mov_b32_e32 v61, v133
	v_mov_b32_e32 v62, v133
	v_mov_b32_e32 v63, v133
	v_mov_b32_e32 v64, v133
	v_mov_b32_e32 v65, v133
	v_mov_b32_e32 v66, v133
	v_mov_b32_e32 v67, v133
	v_mov_b32_e32 v68, v133
	v_mov_b32_e32 v69, v133
	v_mov_b32_e32 v70, v133
	v_mov_b32_e32 v71, v133
	v_mov_b32_e32 v72, v133
	v_mov_b32_e32 v73, v133
	v_mov_b32_e32 v74, v133
	v_mov_b32_e32 v75, v133
	v_mov_b32_e32 v76, v133
	v_mov_b32_e32 v77, v133
	v_mov_b32_e32 v78, v133
	v_mov_b32_e32 v79, v133
	v_mov_b32_e32 v80, v133
	v_mov_b32_e32 v81, v133
	v_mov_b32_e32 v98, v133
	v_mov_b32_e32 v99, v133
	v_mov_b32_e32 v100, v133
	v_mov_b32_e32 v101, v133
	v_mov_b32_e32 v102, v133
	v_mov_b32_e32 v103, v133
	v_mov_b32_e32 v104, v133
	v_mov_b32_e32 v105, v133
	v_mov_b32_e32 v106, v133
	v_mov_b32_e32 v107, v133
	v_mov_b32_e32 v108, v133
	v_mov_b32_e32 v109, v133
	v_mov_b32_e32 v110, v133
	v_mov_b32_e32 v111, v133
	v_mov_b32_e32 v112, v133
	v_mov_b32_e32 v113, v133
	v_mov_b32_e32 v82, v133
	v_mov_b32_e32 v83, v133
	v_mov_b32_e32 v84, v133
	v_mov_b32_e32 v85, v133
	v_mov_b32_e32 v86, v133
	v_mov_b32_e32 v87, v133
	v_mov_b32_e32 v88, v133
	v_mov_b32_e32 v89, v133
	v_mov_b32_e32 v90, v133
	v_mov_b32_e32 v91, v133
	v_mov_b32_e32 v92, v133
	v_mov_b32_e32 v93, v133
	v_mov_b32_e32 v94, v133
	v_mov_b32_e32 v95, v133
	v_mov_b32_e32 v96, v133
	v_mov_b32_e32 v97, v133
	v_mov_b32_e32 v114, v133
	v_mov_b32_e32 v115, v133
	v_mov_b32_e32 v116, v133
	v_mov_b32_e32 v117, v133
	v_mov_b32_e32 v118, v133
	v_mov_b32_e32 v119, v133
	v_mov_b32_e32 v120, v133
	v_mov_b32_e32 v121, v133
	v_mov_b32_e32 v122, v133
	v_mov_b32_e32 v123, v133
	v_mov_b32_e32 v124, v133
	v_mov_b32_e32 v125, v133
	v_mov_b32_e32 v126, v133
	v_mov_b32_e32 v127, v133
	v_mov_b32_e32 v128, v133
	v_mov_b32_e32 v129, v133
	s_barrier
	s_branch .LBB0_754

.LBB0_957:
	s_lshl_b32 s22, s22, 5
	s_and_b32 s69, s22, 0x60
	s_lshl_b32 s68, s31, 6
	s_lshl_b32 s23, s31, 13
	s_lshl_b32 s22, s69, 7
	v_and_b32_e32 v13, 48, v12
	v_lshlrev_b32_e32 v14, 6, v12
	s_movk_i32 s24, 0x3c0
	v_lshlrev_b32_e32 v12, 2, v12
	s_add_u32 s70, s8, 0x4000000
	v_and_or_b32 v13, v14, s24, v13
	v_and_b32_e32 v12, 32, v12
	s_addc_u32 s71, s9, 0
	v_bitop3_b32 v194, s22, v13, v12 bitop3:0xf6
	s_add_u32 s22, s8, 0x1000000
	v_bitop3_b32 v14, v13, s23, v12 bitop3:0xde
	s_addc_u32 s23, s9, 0
	s_add_u32 s24, s8, 0xc000000
	s_addc_u32 s25, s9, 0
	s_add_i32 m0, s62, 0x18000
	v_lshl_add_u64 v[0:1], v[0:1], 0, s[16:17]
	global_load_lds_dwordx4 v[0:1], off
	v_lshl_add_u64 v[0:1], v[2:3], 0, s[16:17]
	s_add_i32 m0, s62, 0x1a000
	s_add_i32 s72, s62, 0x8000
	global_load_lds_dwordx4 v[0:1], off
	v_lshl_add_u64 v[0:1], v[8:9], 0, s[16:17]
	s_mov_b32 m0, s72
	s_add_i32 s73, s62, 0xa000
	global_load_lds_dwordx4 v[0:1], off
	v_lshl_add_u64 v[0:1], v[10:11], 0, s[16:17]
	s_mov_b32 m0, s73
	s_mov_b32 s83, 0
	global_load_lds_dwordx4 v[0:1], off
	s_add_i32 m0, s62, 0x1c000
	v_lshl_add_u64 v[0:1], v[4:5], 0, s[16:17]
	global_load_lds_dwordx4 v[0:1], off
	v_lshl_add_u64 v[0:1], v[6:7], 0, s[16:17]
	s_add_i32 m0, s62, 0x1e000
	s_cmpk_lt_u32 s29, 0x100
	global_load_lds_dwordx4 v[0:1], off
	s_waitcnt vmcnt(8)
	s_barrier
	s_cselect_b64 s[26:27], -1, 0
	s_lshl_b32 s29, s69, 2
	s_add_i32 s74, s28, s29
	s_lshl_b32 s29, s31, 8
	s_lshl_b32 s31, -1, s61
	s_add_i32 s75, s28, s29
	s_lshl_b64 s[28:29], s[56:57], 8
	s_not_b32 s76, s31
	s_waitcnt vmcnt(6)
	s_and_b64 s[12:13], s[12:13], exec
	s_cselect_b32 s77, 25, 24
	s_lshl_b32 s12, -1, s60
	s_not_b32 s78, s12
	s_sub_i32 s79, 14, s53
	s_lshl_b32 s80, s30, 3
	v_add_u32_e32 v195, 0, v14
	s_cmp_eq_u32 s100, 0
	s_cbranch_scc1 .Lrt_done
	v_add_f32_e32 v213, v201, v200
	v_add_f32_e32 v214, v202, v203
	v_add_f32_e32 v213, v213, v214
	v_fmamk_f32 v213, v213, 0x3a800000, v172
	v_cmp_gt_f32_e32 vcc, s33, v213
	v_mul_f32_e32 v214, 0x4b800000, v213
	s_nop 0
	v_cndmask_b32_e32 v213, v213, v214, vcc
	v_rsq_f32_e32 v213, v213
	s_nop 0
	v_mul_f32_e32 v214, 0x45800000, v213
	v_cndmask_b32_e32 v213, v213, v214, vcc
	ds_write_b32 v212, v213
	v_add_u32_e32 v212, 0x800, v212
	v_add_f32_e32 v213, v205, v204
	v_add_f32_e32 v214, v206, v207
	v_add_f32_e32 v213, v213, v214
	v_fmamk_f32 v213, v213, 0x3a800000, v172
	v_cmp_gt_f32_e32 vcc, s33, v213
	v_mul_f32_e32 v214, 0x4b800000, v213
	s_nop 0
	v_cndmask_b32_e32 v213, v213, v214, vcc
	v_rsq_f32_e32 v213, v213
	s_nop 0
	v_mul_f32_e32 v214, 0x45800000, v213
	v_cndmask_b32_e32 v213, v213, v214, vcc
	ds_write_b32 v212, v213
	v_add_u32_e32 v212, 0x800, v212
	s_cmp_eq_u32 s100, 2
	s_cbranch_scc1 .Lrt_fin
	v_add_f32_e32 v213, v209, v208
	v_add_f32_e32 v214, v210, v211
	v_add_f32_e32 v213, v213, v214
	v_fmamk_f32 v213, v213, 0x3a800000, v172
	v_cmp_gt_f32_e32 vcc, s33, v213
	v_mul_f32_e32 v214, 0x4b800000, v213
	s_nop 0
	v_cndmask_b32_e32 v213, v213, v214, vcc
	v_rsq_f32_e32 v213, v213
	s_nop 0
	v_mul_f32_e32 v214, 0x45800000, v213
	v_cndmask_b32_e32 v213, v213, v214, vcc
	ds_write_b32 v212, v213
	v_add_u32_e32 v212, 0x800, v212

.LBB0_1502:
	v_and_b32_e32 v19, 48, v12
	v_lshlrev_b32_e32 v20, 6, v12
	s_movk_i32 s1, 0x3c0
	v_lshlrev_b32_e32 v12, 2, v12
	s_mov_b64 s[18:19], 0x80
	s_and_b32 s39, s33, 3
	s_lshl_b32 s0, s38, 13
	v_and_or_b32 v19, v20, s1, v19
	v_and_b32_e32 v12, 32, v12
	s_add_i32 m0, s13, 0x18000
	v_lshl_add_u64 v[10:11], v[10:11], 0, s[18:19]
	s_lshl_b32 s44, s38, 6
	v_bitop3_b32 v20, v19, s0, v12 bitop3:0xde
	s_lshl_b32 s0, s39, 12
	global_load_lds_dwordx4 v[10:11], off
	v_lshl_add_u64 v[8:9], v[8:9], 0, s[18:19]
	s_add_i32 m0, s13, 0x1a000
	s_add_i32 s48, s13, 0x8000
	s_add_i32 s49, s13, 0xa000
	global_load_lds_dwordx4 v[8:9], off
	v_lshl_add_u64 v[6:7], v[6:7], 0, s[18:19]
	s_mov_b32 m0, s48
	s_add_u32 s4, s26, 0x80080
	global_load_lds_dwordx4 v[6:7], off
	v_lshl_add_u64 v[4:5], v[4:5], 0, s[18:19]
	s_mov_b32 m0, s49
	s_addc_u32 s5, s27, 0
	global_load_lds_dwordx4 v[4:5], off
	s_add_i32 m0, s13, 0x1c000
	v_lshl_add_u64 v[4:5], s[4:5], 0, v[2:3]
	global_load_lds_dwordx4 v[4:5], off
	v_lshl_add_u64 v[4:5], s[4:5], 0, v[134:135]
	s_add_i32 m0, s13, 0x1e000
	v_bitop3_b32 v148, v19, s0, v12 bitop3:0xde
	global_load_lds_dwordx4 v[4:5], off
	s_waitcnt vmcnt(8)
	s_barrier
	v_lshlrev_b32_e32 v4, 15, v13
	v_and_b32_e32 v4, 0xffff0000, v4
	v_lshl_add_u32 v4, v14, 12, v4
	v_and_b32_e32 v5, 1, v13
	v_lshl_or_b32 v4, v5, 6, v4
	s_mov_b64 s[0:1], 0x80080
	v_lshl_add_u32 v4, v15, 1, v4
	v_mov_b32_e32 v5, v3
	v_lshl_add_u64 v[136:137], v[4:5], 0, s[0:1]
	v_lshlrev_b32_e32 v4, 15, v16
	v_and_b32_e32 v4, 0xffff0000, v4
	v_lshl_add_u32 v4, v17, 12, v4
	v_and_b32_e32 v5, 1, v16
	s_waitcnt vmcnt(6)
	v_lshl_or_b32 v4, v5, 6, v4
	v_lshl_add_u32 v4, v18, 1, v4
	v_mov_b32_e32 v5, v3
	v_lshl_add_u64 v[138:139], v[4:5], 0, s[0:1]
	v_mov_b64_e32 v[140:141], 0x100
	v_mov_b64_e32 v[142:143], 0xff
	s_add_i32 s50, 0, 0x10000
	s_add_i32 s51, 0, 0x14000
	v_add_u32_e32 v149, 0, v20
	v_mov_b32_e32 v4, v3
	v_mov_b32_e32 v6, v3
	v_mov_b32_e32 v7, v3
	v_mov_b32_e32 v8, v3
	v_mov_b32_e32 v9, v3
	v_mov_b32_e32 v10, v3
	v_mov_b32_e32 v11, v3
	v_mov_b32_e32 v16, v3
	v_mov_b32_e32 v17, v3
	v_mov_b32_e32 v18, v3
	v_mov_b32_e32 v19, v3
	v_mov_b32_e32 v24, v3
	v_mov_b32_e32 v25, v3
	v_mov_b32_e32 v26, v3
	v_mov_b32_e32 v27, v3
	v_mov_b32_e32 v32, v3
	v_mov_b32_e32 v33, v3
	v_mov_b32_e32 v34, v3
	v_mov_b32_e32 v35, v3
	v_mov_b32_e32 v40, v3
	v_mov_b32_e32 v41, v3
	v_mov_b32_e32 v42, v3
	v_mov_b32_e32 v43, v3
	v_mov_b32_e32 v48, v3
	v_mov_b32_e32 v49, v3
	v_mov_b32_e32 v50, v3
	v_mov_b32_e32 v51, v3
	v_mov_b32_e32 v56, v3
	v_mov_b32_e32 v57, v3
	v_mov_b32_e32 v58, v3
	v_mov_b32_e32 v59, v3
	v_mov_b32_e32 v12, v3
	v_mov_b32_e32 v13, v3
	v_mov_b32_e32 v14, v3
	v_mov_b32_e32 v15, v3
	v_mov_b32_e32 v20, v3
	v_mov_b32_e32 v21, v3
	v_mov_b32_e32 v22, v3
	v_mov_b32_e32 v23, v3
	v_mov_b32_e32 v28, v3
	v_mov_b32_e32 v29, v3
	v_mov_b32_e32 v30, v3
	v_mov_b32_e32 v31, v3
	v_mov_b32_e32 v36, v3
	v_mov_b32_e32 v37, v3
	v_mov_b32_e32 v38, v3
	v_mov_b32_e32 v39, v3
	v_mov_b32_e32 v44, v3
	v_mov_b32_e32 v45, v3
	v_mov_b32_e32 v46, v3
	v_mov_b32_e32 v47, v3
	v_mov_b32_e32 v52, v3
	v_mov_b32_e32 v53, v3
	v_mov_b32_e32 v54, v3
	v_mov_b32_e32 v55, v3
	v_mov_b32_e32 v60, v3
	v_mov_b32_e32 v61, v3
	v_mov_b32_e32 v62, v3
	v_mov_b32_e32 v63, v3
	v_mov_b32_e32 v64, v3
	v_mov_b32_e32 v65, v3
	v_mov_b32_e32 v66, v3
	v_mov_b32_e32 v67, v3
	v_mov_b32_e32 v68, v3
	v_mov_b32_e32 v69, v3
	v_mov_b32_e32 v70, v3
	v_mov_b32_e32 v71, v3
	v_mov_b32_e32 v72, v3
	v_mov_b32_e32 v73, v3
	v_mov_b32_e32 v74, v3
	v_mov_b32_e32 v75, v3
	v_mov_b32_e32 v80, v3
	v_mov_b32_e32 v81, v3
	v_mov_b32_e32 v82, v3
	v_mov_b32_e32 v83, v3
	v_mov_b32_e32 v88, v3
	v_mov_b32_e32 v89, v3
	v_mov_b32_e32 v90, v3
	v_mov_b32_e32 v91, v3
	v_mov_b32_e32 v96, v3
	v_mov_b32_e32 v97, v3
	v_mov_b32_e32 v98, v3
	v_mov_b32_e32 v99, v3
	v_mov_b32_e32 v104, v3
	v_mov_b32_e32 v105, v3
	v_mov_b32_e32 v106, v3
	v_mov_b32_e32 v107, v3
	v_mov_b32_e32 v112, v3
	v_mov_b32_e32 v113, v3
	v_mov_b32_e32 v114, v3
	v_mov_b32_e32 v115, v3
	v_mov_b32_e32 v120, v3
	v_mov_b32_e32 v121, v3
	v_mov_b32_e32 v122, v3
	v_mov_b32_e32 v123, v3
	v_mov_b32_e32 v76, v3
	v_mov_b32_e32 v77, v3
	v_mov_b32_e32 v78, v3
	v_mov_b32_e32 v79, v3
	v_mov_b32_e32 v84, v3
	v_mov_b32_e32 v85, v3
	v_mov_b32_e32 v86, v3
	v_mov_b32_e32 v87, v3
	v_mov_b32_e32 v92, v3
	v_mov_b32_e32 v93, v3
	v_mov_b32_e32 v94, v3
	v_mov_b32_e32 v95, v3
	v_mov_b32_e32 v100, v3
	v_mov_b32_e32 v101, v3
	v_mov_b32_e32 v102, v3
	v_mov_b32_e32 v103, v3
	v_mov_b32_e32 v108, v3
	v_mov_b32_e32 v109, v3
	v_mov_b32_e32 v110, v3
	v_mov_b32_e32 v111, v3
	v_mov_b32_e32 v116, v3
	v_mov_b32_e32 v117, v3
	v_mov_b32_e32 v118, v3
	v_mov_b32_e32 v119, v3
	v_mov_b32_e32 v124, v3
	v_mov_b32_e32 v125, v3
	v_mov_b32_e32 v126, v3
	v_mov_b32_e32 v127, v3
	v_mov_b32_e32 v128, v3
	v_mov_b32_e32 v129, v3
	v_mov_b32_e32 v130, v3
	v_mov_b32_e32 v131, v3
	s_barrier
	s_branch .LBB0_1504
